# HGRN2 state-update K operand via transposing LDS reads of the k-tile (no transposed image), trimmed elementwise part (kept 1-k factors, exec-masked segment prefix), next score tile fetched under the c
# speedup vs baseline: 1.0835x; 1.0021x over previous
.Lhg_rel0:
	s_or_b64 exec, exec, s[38:39]
	s_waitcnt vmcnt(16)
	v_lshlrev_b32_e32 v76, 16, v10
	v_and_b32_e32 v77, 0xffff0000, v10
	v_lshlrev_b32_e32 v78, 16, v11
	v_and_b32_e32 v79, 0xffff0000, v11
	v_lshlrev_b32_e32 v80, 16, v12
	v_and_b32_e32 v81, 0xffff0000, v12
	v_lshlrev_b32_e32 v82, 16, v13
	v_and_b32_e32 v83, 0xffff0000, v13
	v_lshlrev_b32_e32 v84, 16, v14
	v_and_b32_e32 v85, 0xffff0000, v14
	v_lshlrev_b32_e32 v86, 16, v15
	v_and_b32_e32 v87, 0xffff0000, v15
	v_lshlrev_b32_e32 v88, 16, v16
	v_and_b32_e32 v89, 0xffff0000, v16
	v_lshlrev_b32_e32 v90, 16, v17
	v_and_b32_e32 v91, 0xffff0000, v17
	v_lshlrev_b32_e32 v92, 16, v18
	v_and_b32_e32 v93, 0xffff0000, v18
	v_lshlrev_b32_e32 v94, 16, v19
	v_and_b32_e32 v95, 0xffff0000, v19
	v_lshlrev_b32_e32 v96, 16, v20
	v_and_b32_e32 v97, 0xffff0000, v20
	v_lshlrev_b32_e32 v98, 16, v21
	v_and_b32_e32 v99, 0xffff0000, v21
	v_lshlrev_b32_e32 v100, 16, v22
	v_and_b32_e32 v101, 0xffff0000, v22
	v_lshlrev_b32_e32 v102, 16, v23
	v_and_b32_e32 v103, 0xffff0000, v23
	v_lshlrev_b32_e32 v104, 16, v24
	v_and_b32_e32 v105, 0xffff0000, v24
	v_lshlrev_b32_e32 v106, 16, v25
	v_and_b32_e32 v107, 0xffff0000, v25
	v_pk_add_f32 v[140:141], v[76:77], 1.0 op_sel_hi:[1,0] neg_lo:[1,0] neg_hi:[1,0]
	v_pk_add_f32 v[142:143], v[78:79], 1.0 op_sel_hi:[1,0] neg_lo:[1,0] neg_hi:[1,0]
	v_pk_add_f32 v[226:227], v[80:81], 1.0 op_sel_hi:[1,0] neg_lo:[1,0] neg_hi:[1,0]
	v_pk_add_f32 v[228:229], v[82:83], 1.0 op_sel_hi:[1,0] neg_lo:[1,0] neg_hi:[1,0]
	v_pk_mul_f32 v[144:145], v[140:141], v[226:227]
	v_pk_mul_f32 v[146:147], v[142:143], v[228:229]
	v_pk_add_f32 v[230:231], v[84:85], 1.0 op_sel_hi:[1,0] neg_lo:[1,0] neg_hi:[1,0]
	v_pk_add_f32 v[232:233], v[86:87], 1.0 op_sel_hi:[1,0] neg_lo:[1,0] neg_hi:[1,0]
	v_pk_mul_f32 v[148:149], v[144:145], v[230:231]
	v_pk_mul_f32 v[150:151], v[146:147], v[232:233]
	v_pk_add_f32 v[234:235], v[88:89], 1.0 op_sel_hi:[1,0] neg_lo:[1,0] neg_hi:[1,0]
	v_pk_add_f32 v[236:237], v[90:91], 1.0 op_sel_hi:[1,0] neg_lo:[1,0] neg_hi:[1,0]
	v_pk_mul_f32 v[152:153], v[148:149], v[234:235]
	v_pk_mul_f32 v[154:155], v[150:151], v[236:237]
	v_pk_add_f32 v[238:239], v[92:93], 1.0 op_sel_hi:[1,0] neg_lo:[1,0] neg_hi:[1,0]
	v_pk_add_f32 v[240:241], v[94:95], 1.0 op_sel_hi:[1,0] neg_lo:[1,0] neg_hi:[1,0]
	v_pk_mul_f32 v[156:157], v[152:153], v[238:239]
	v_pk_mul_f32 v[158:159], v[154:155], v[240:241]
	v_pk_add_f32 v[242:243], v[96:97], 1.0 op_sel_hi:[1,0] neg_lo:[1,0] neg_hi:[1,0]
	v_pk_add_f32 v[244:245], v[98:99], 1.0 op_sel_hi:[1,0] neg_lo:[1,0] neg_hi:[1,0]
	v_pk_mul_f32 v[160:161], v[156:157], v[242:243]
	v_pk_mul_f32 v[162:163], v[158:159], v[244:245]
	v_pk_add_f32 v[246:247], v[100:101], 1.0 op_sel_hi:[1,0] neg_lo:[1,0] neg_hi:[1,0]
	v_pk_add_f32 v[248:249], v[102:103], 1.0 op_sel_hi:[1,0] neg_lo:[1,0] neg_hi:[1,0]
	v_pk_mul_f32 v[164:165], v[160:161], v[246:247]
	v_pk_mul_f32 v[166:167], v[162:163], v[248:249]
	v_pk_add_f32 v[74:75], v[104:105], 1.0 op_sel_hi:[1,0] neg_lo:[1,0] neg_hi:[1,0]
	v_pk_add_f32 v[172:173], v[106:107], 1.0 op_sel_hi:[1,0] neg_lo:[1,0] neg_hi:[1,0]
	v_pk_mul_f32 v[168:169], v[164:165], v[74:75]
	v_pk_mul_f32 v[170:171], v[166:167], v[172:173]
	ds_write_b128 v6, v[168:171]
	ds_read_b128 v[192:195], v7
	ds_read_b128 v[196:199], v7 offset:128
	ds_read_b128 v[200:203], v7 offset:256
	ds_read_b128 v[204:207], v7 offset:384
	ds_read_b128 v[208:211], v7 offset:512
	ds_read_b128 v[212:215], v7 offset:640
	ds_read_b128 v[216:219], v7 offset:768
	v_lshlrev_b32_e32 v108, 16, v26
	v_and_b32_e32 v109, 0xffff0000, v26
	v_lshlrev_b32_e32 v110, 16, v27
	v_and_b32_e32 v111, 0xffff0000, v27
	v_lshlrev_b32_e32 v112, 16, v28
	v_and_b32_e32 v113, 0xffff0000, v28
	v_lshlrev_b32_e32 v114, 16, v29
	v_and_b32_e32 v115, 0xffff0000, v29
	v_lshlrev_b32_e32 v116, 16, v30
	v_and_b32_e32 v117, 0xffff0000, v30
	v_lshlrev_b32_e32 v118, 16, v31
	v_and_b32_e32 v119, 0xffff0000, v31
	v_lshlrev_b32_e32 v120, 16, v32
	v_and_b32_e32 v121, 0xffff0000, v32
	v_lshlrev_b32_e32 v122, 16, v33
	v_and_b32_e32 v123, 0xffff0000, v33
	v_lshlrev_b32_e32 v124, 16, v34
	v_and_b32_e32 v125, 0xffff0000, v34
	v_lshlrev_b32_e32 v126, 16, v35
	v_and_b32_e32 v127, 0xffff0000, v35
	v_lshlrev_b32_e32 v128, 16, v36
	v_and_b32_e32 v129, 0xffff0000, v36
	v_lshlrev_b32_e32 v130, 16, v37
	v_and_b32_e32 v131, 0xffff0000, v37
	v_lshlrev_b32_e32 v132, 16, v38
	v_and_b32_e32 v133, 0xffff0000, v38
	v_lshlrev_b32_e32 v134, 16, v39
	v_and_b32_e32 v135, 0xffff0000, v39
	v_lshlrev_b32_e32 v136, 16, v40
	v_and_b32_e32 v137, 0xffff0000, v40
	v_lshlrev_b32_e32 v138, 16, v41
	v_and_b32_e32 v139, 0xffff0000, v41
	global_load_dwordx2 v[10:11], v3, s[8:9]
	global_load_dwordx2 v[26:27], v2, s[8:9]
	s_add_u32 s8, s8, s10
	s_addc_u32 s9, s9, s11
	global_load_dwordx2 v[12:13], v3, s[8:9]
	global_load_dwordx2 v[28:29], v2, s[8:9]
	s_add_u32 s8, s8, s10
	s_addc_u32 s9, s9, s11
	global_load_dwordx2 v[14:15], v3, s[8:9]
	global_load_dwordx2 v[30:31], v2, s[8:9]
	s_add_u32 s8, s8, s10
	s_addc_u32 s9, s9, s11
	global_load_dwordx2 v[16:17], v3, s[8:9]
	global_load_dwordx2 v[32:33], v2, s[8:9]
	s_add_u32 s8, s8, s10
	s_addc_u32 s9, s9, s11
	global_load_dwordx2 v[18:19], v3, s[8:9]
	global_load_dwordx2 v[34:35], v2, s[8:9]
	s_add_u32 s8, s8, s10
	s_addc_u32 s9, s9, s11
	global_load_dwordx2 v[20:21], v3, s[8:9]
	global_load_dwordx2 v[36:37], v2, s[8:9]
	s_add_u32 s8, s8, s10
	s_addc_u32 s9, s9, s11
	global_load_dwordx2 v[22:23], v3, s[8:9]
	global_load_dwordx2 v[38:39], v2, s[8:9]
	s_add_u32 s8, s8, s10
	s_addc_u32 s9, s9, s11
	global_load_dwordx2 v[24:25], v3, s[8:9]
	global_load_dwordx2 v[40:41], v2, s[8:9]
	s_add_u32 s8, s8, s10
	s_addc_u32 s9, s9, s11
	s_cmp_lt_u32 s16, 63
	s_cselect_b32 s34, s12, s14
	s_cselect_b32 s35, s13, s15
	s_add_u32 s8, s8, s34
	s_addc_u32 s9, s9, s35
	s_add_i32 s16, s16, 1
	v_mov_b32_e32 v176, 1.0
	v_mov_b32_e32 v177, 1.0
	v_mov_b32_e32 v178, 1.0
	v_mov_b32_e32 v179, 1.0
	s_mov_b64 s[34:35], exec
	s_waitcnt lgkmcnt(6)
	s_mov_b64 exec, s[18:19]
	v_pk_mul_f32 v[176:177], v[176:177], v[192:193]
	v_pk_mul_f32 v[178:179], v[178:179], v[194:195]
	s_waitcnt lgkmcnt(5)
	s_mov_b64 exec, s[20:21]
	v_pk_mul_f32 v[176:177], v[176:177], v[196:197]
	v_pk_mul_f32 v[178:179], v[178:179], v[198:199]
	s_waitcnt lgkmcnt(4)
	s_mov_b64 exec, s[22:23]
	v_pk_mul_f32 v[176:177], v[176:177], v[200:201]
	v_pk_mul_f32 v[178:179], v[178:179], v[202:203]
	s_waitcnt lgkmcnt(3)
	s_mov_b64 exec, s[24:25]
	v_pk_mul_f32 v[176:177], v[176:177], v[204:205]
	v_pk_mul_f32 v[178:179], v[178:179], v[206:207]
	s_waitcnt lgkmcnt(2)
	s_mov_b64 exec, s[26:27]
	v_pk_mul_f32 v[176:177], v[176:177], v[208:209]
	v_pk_mul_f32 v[178:179], v[178:179], v[210:211]
	s_waitcnt lgkmcnt(1)
	s_mov_b64 exec, s[28:29]
	v_pk_mul_f32 v[176:177], v[176:177], v[212:213]
	v_pk_mul_f32 v[178:179], v[178:179], v[214:215]
	s_waitcnt lgkmcnt(0)
	s_mov_b64 exec, s[30:31]
	v_pk_mul_f32 v[176:177], v[176:177], v[216:217]
	v_pk_mul_f32 v[178:179], v[178:179], v[218:219]
	s_mov_b64 exec, s[34:35]
	v_pk_mul_f32 v[188:189], v[176:177], v[168:169]
	v_pk_mul_f32 v[190:191], v[178:179], v[170:171]
	s_mov_b64 s[34:35], exec
	s_mov_b64 exec, s[30:31]
	ds_write_b128 v8, v[188:191]
	s_mov_b64 exec, s[34:35]
	v_max_f32_e32 v180, 0xda24260, v188
	v_max_f32_e32 v181, 0xda24260, v189
	v_max_f32_e32 v182, 0xda24260, v190
	v_max_f32_e32 v183, 0xda24260, v191
	v_rcp_f32_e32 v180, v180
	v_rcp_f32_e32 v181, v181
	v_rcp_f32_e32 v182, v182
	v_rcp_f32_e32 v183, v183
	v_pk_mul_f32 v[192:193], v[136:137], v[188:189]
	v_pk_mul_f32 v[194:195], v[138:139], v[190:191]
	v_pk_mul_f32 v[196:197], v[104:105], v[180:181]
	v_pk_mul_f32 v[198:199], v[106:107], v[182:183]
	v_cvt_pk_bf16_f32 v204, v192, v193
	v_cvt_pk_bf16_f32 v205, v194, v195
	ds_write_b64 v4, v[204:205] offset:2016
	v_cvt_pk_bf16_f32 v206, v196, v197
	v_cvt_pk_bf16_f32 v207, v198, v199
	ds_write_b64 v4, v[206:207] offset:38880
	v_pk_mul_f32 v[180:181], v[180:181], v[74:75]
	v_pk_mul_f32 v[182:183], v[182:183], v[172:173]
	v_pk_mul_f32 v[188:189], v[176:177], v[164:165]
	v_pk_mul_f32 v[190:191], v[178:179], v[166:167]
	v_pk_mul_f32 v[192:193], v[132:133], v[188:189]
	v_pk_mul_f32 v[194:195], v[134:135], v[190:191]
	v_pk_mul_f32 v[200:201], v[100:101], v[180:181]
	v_pk_mul_f32 v[202:203], v[102:103], v[182:183]
	v_cvt_pk_bf16_f32 v204, v192, v193
	v_cvt_pk_bf16_f32 v205, v194, v195
	ds_write_b64 v4, v[204:205] offset:1728
	v_cvt_pk_bf16_f32 v206, v200, v201
	v_cvt_pk_bf16_f32 v207, v202, v203
	ds_write_b64 v4, v[206:207] offset:38592
	v_pk_mul_f32 v[180:181], v[180:181], v[246:247]
	v_pk_mul_f32 v[182:183], v[182:183], v[248:249]
	v_pk_mul_f32 v[188:189], v[176:177], v[160:161]
	v_pk_mul_f32 v[190:191], v[178:179], v[162:163]
	v_pk_mul_f32 v[192:193], v[128:129], v[188:189]
	v_pk_mul_f32 v[194:195], v[130:131], v[190:191]
	v_pk_mul_f32 v[196:197], v[96:97], v[180:181]
	v_pk_mul_f32 v[198:199], v[98:99], v[182:183]
	v_cvt_pk_bf16_f32 v204, v192, v193
	v_cvt_pk_bf16_f32 v205, v194, v195
	ds_write_b64 v4, v[204:205] offset:1440
	v_cvt_pk_bf16_f32 v206, v196, v197
	v_cvt_pk_bf16_f32 v207, v198, v199
	ds_write_b64 v4, v[206:207] offset:38304
	v_pk_mul_f32 v[180:181], v[180:181], v[242:243]
	v_pk_mul_f32 v[182:183], v[182:183], v[244:245]
	v_pk_mul_f32 v[188:189], v[176:177], v[156:157]
	v_pk_mul_f32 v[190:191], v[178:179], v[158:159]
	v_pk_mul_f32 v[192:193], v[124:125], v[188:189]
	v_pk_mul_f32 v[194:195], v[126:127], v[190:191]
	v_pk_mul_f32 v[200:201], v[92:93], v[180:181]
	v_pk_mul_f32 v[202:203], v[94:95], v[182:183]
	v_cvt_pk_bf16_f32 v204, v192, v193
	v_cvt_pk_bf16_f32 v205, v194, v195
	ds_write_b64 v4, v[204:205] offset:1152
	v_cvt_pk_bf16_f32 v206, v200, v201
	v_cvt_pk_bf16_f32 v207, v202, v203
	ds_write_b64 v4, v[206:207] offset:38016
	v_pk_mul_f32 v[180:181], v[180:181], v[238:239]
	v_pk_mul_f32 v[182:183], v[182:183], v[240:241]
	v_pk_mul_f32 v[188:189], v[176:177], v[152:153]
	v_pk_mul_f32 v[190:191], v[178:179], v[154:155]
	v_pk_mul_f32 v[192:193], v[120:121], v[188:189]
	v_pk_mul_f32 v[194:195], v[122:123], v[190:191]
	v_pk_mul_f32 v[196:197], v[88:89], v[180:181]
	v_pk_mul_f32 v[198:199], v[90:91], v[182:183]
	v_cvt_pk_bf16_f32 v204, v192, v193
	v_cvt_pk_bf16_f32 v205, v194, v195
	ds_write_b64 v4, v[204:205] offset:864
	v_cvt_pk_bf16_f32 v206, v196, v197
	v_cvt_pk_bf16_f32 v207, v198, v199
	ds_write_b64 v4, v[206:207] offset:37728
	v_pk_mul_f32 v[180:181], v[180:181], v[234:235]
	v_pk_mul_f32 v[182:183], v[182:183], v[236:237]
	v_pk_mul_f32 v[188:189], v[176:177], v[148:149]
	v_pk_mul_f32 v[190:191], v[178:179], v[150:151]
	v_pk_mul_f32 v[192:193], v[116:117], v[188:189]
	v_pk_mul_f32 v[194:195], v[118:119], v[190:191]
	v_pk_mul_f32 v[200:201], v[84:85], v[180:181]
	v_pk_mul_f32 v[202:203], v[86:87], v[182:183]
	v_cvt_pk_bf16_f32 v204, v192, v193
	v_cvt_pk_bf16_f32 v205, v194, v195
	ds_write_b64 v4, v[204:205] offset:576
	v_cvt_pk_bf16_f32 v206, v200, v201
	v_cvt_pk_bf16_f32 v207, v202, v203
	ds_write_b64 v4, v[206:207] offset:37440
	v_pk_mul_f32 v[180:181], v[180:181], v[230:231]
	v_pk_mul_f32 v[182:183], v[182:183], v[232:233]
	v_pk_mul_f32 v[188:189], v[176:177], v[144:145]
	v_pk_mul_f32 v[190:191], v[178:179], v[146:147]
	v_pk_mul_f32 v[192:193], v[112:113], v[188:189]
	v_pk_mul_f32 v[194:195], v[114:115], v[190:191]
	v_pk_mul_f32 v[196:197], v[80:81], v[180:181]
	v_pk_mul_f32 v[198:199], v[82:83], v[182:183]
	v_cvt_pk_bf16_f32 v204, v192, v193
	v_cvt_pk_bf16_f32 v205, v194, v195
	ds_write_b64 v4, v[204:205] offset:288
	v_cvt_pk_bf16_f32 v206, v196, v197
	v_cvt_pk_bf16_f32 v207, v198, v199
	ds_write_b64 v4, v[206:207] offset:37152
	v_pk_mul_f32 v[180:181], v[180:181], v[226:227]
	v_pk_mul_f32 v[182:183], v[182:183], v[228:229]
	v_pk_mul_f32 v[188:189], v[176:177], v[140:141]
	v_pk_mul_f32 v[190:191], v[178:179], v[142:143]
	v_pk_mul_f32 v[192:193], v[108:109], v[188:189]
	v_pk_mul_f32 v[194:195], v[110:111], v[190:191]
	v_pk_mul_f32 v[200:201], v[76:77], v[180:181]
	v_pk_mul_f32 v[202:203], v[78:79], v[182:183]
	v_cvt_pk_bf16_f32 v204, v192, v193
	v_cvt_pk_bf16_f32 v205, v194, v195
	ds_write_b64 v4, v[204:205]
	v_cvt_pk_bf16_f32 v206, v200, v201
	v_cvt_pk_bf16_f32 v207, v202, v203
	ds_write_b64 v4, v[206:207] offset:36864
	s_waitcnt lgkmcnt(0)
	s_barrier
	s_mov_b32 s17, 31
.Lhg_ploop:
	s_waitcnt vmcnt(16)
	v_lshlrev_b32_e32 v76, 16, v42
	v_and_b32_e32 v77, 0xffff0000, v42
	v_lshlrev_b32_e32 v78, 16, v43
	v_and_b32_e32 v79, 0xffff0000, v43
	v_lshlrev_b32_e32 v80, 16, v44
	v_and_b32_e32 v81, 0xffff0000, v44
	v_lshlrev_b32_e32 v82, 16, v45
	v_and_b32_e32 v83, 0xffff0000, v45
	v_lshlrev_b32_e32 v84, 16, v46
	v_and_b32_e32 v85, 0xffff0000, v46
	v_lshlrev_b32_e32 v86, 16, v47
	v_and_b32_e32 v87, 0xffff0000, v47
	v_lshlrev_b32_e32 v88, 16, v48
	v_and_b32_e32 v89, 0xffff0000, v48
	v_lshlrev_b32_e32 v90, 16, v49
	v_and_b32_e32 v91, 0xffff0000, v49
	v_lshlrev_b32_e32 v92, 16, v50
	v_and_b32_e32 v93, 0xffff0000, v50
	v_lshlrev_b32_e32 v94, 16, v51
	v_and_b32_e32 v95, 0xffff0000, v51
	v_lshlrev_b32_e32 v96, 16, v52
	v_and_b32_e32 v97, 0xffff0000, v52
	v_lshlrev_b32_e32 v98, 16, v53
	v_and_b32_e32 v99, 0xffff0000, v53
	v_lshlrev_b32_e32 v100, 16, v54
	v_and_b32_e32 v101, 0xffff0000, v54
	v_lshlrev_b32_e32 v102, 16, v55
	v_and_b32_e32 v103, 0xffff0000, v55
	v_lshlrev_b32_e32 v104, 16, v56
	v_and_b32_e32 v105, 0xffff0000, v56
	v_lshlrev_b32_e32 v106, 16, v57
	v_and_b32_e32 v107, 0xffff0000, v57
	v_pk_add_f32 v[140:141], v[76:77], 1.0 op_sel_hi:[1,0] neg_lo:[1,0] neg_hi:[1,0]
	v_pk_add_f32 v[142:143], v[78:79], 1.0 op_sel_hi:[1,0] neg_lo:[1,0] neg_hi:[1,0]
	v_pk_add_f32 v[226:227], v[80:81], 1.0 op_sel_hi:[1,0] neg_lo:[1,0] neg_hi:[1,0]
	v_pk_add_f32 v[228:229], v[82:83], 1.0 op_sel_hi:[1,0] neg_lo:[1,0] neg_hi:[1,0]
	v_pk_mul_f32 v[144:145], v[140:141], v[226:227]
	v_pk_mul_f32 v[146:147], v[142:143], v[228:229]
	v_pk_add_f32 v[230:231], v[84:85], 1.0 op_sel_hi:[1,0] neg_lo:[1,0] neg_hi:[1,0]
	v_pk_add_f32 v[232:233], v[86:87], 1.0 op_sel_hi:[1,0] neg_lo:[1,0] neg_hi:[1,0]
	v_pk_mul_f32 v[148:149], v[144:145], v[230:231]
	v_pk_mul_f32 v[150:151], v[146:147], v[232:233]
	v_pk_add_f32 v[234:235], v[88:89], 1.0 op_sel_hi:[1,0] neg_lo:[1,0] neg_hi:[1,0]
	v_pk_add_f32 v[236:237], v[90:91], 1.0 op_sel_hi:[1,0] neg_lo:[1,0] neg_hi:[1,0]
	v_pk_mul_f32 v[152:153], v[148:149], v[234:235]
	v_pk_mul_f32 v[154:155], v[150:151], v[236:237]
	v_pk_add_f32 v[238:239], v[92:93], 1.0 op_sel_hi:[1,0] neg_lo:[1,0] neg_hi:[1,0]
	v_pk_add_f32 v[240:241], v[94:95], 1.0 op_sel_hi:[1,0] neg_lo:[1,0] neg_hi:[1,0]
	v_pk_mul_f32 v[156:157], v[152:153], v[238:239]
	v_pk_mul_f32 v[158:159], v[154:155], v[240:241]
	v_pk_add_f32 v[242:243], v[96:97], 1.0 op_sel_hi:[1,0] neg_lo:[1,0] neg_hi:[1,0]
	v_pk_add_f32 v[244:245], v[98:99], 1.0 op_sel_hi:[1,0] neg_lo:[1,0] neg_hi:[1,0]
	v_pk_mul_f32 v[160:161], v[156:157], v[242:243]
	v_pk_mul_f32 v[162:163], v[158:159], v[244:245]
	v_pk_add_f32 v[246:247], v[100:101], 1.0 op_sel_hi:[1,0] neg_lo:[1,0] neg_hi:[1,0]
	v_pk_add_f32 v[248:249], v[102:103], 1.0 op_sel_hi:[1,0] neg_lo:[1,0] neg_hi:[1,0]
	v_pk_mul_f32 v[164:165], v[160:161], v[246:247]
	v_pk_mul_f32 v[166:167], v[162:163], v[248:249]
	v_pk_add_f32 v[74:75], v[104:105], 1.0 op_sel_hi:[1,0] neg_lo:[1,0] neg_hi:[1,0]
	v_pk_add_f32 v[172:173], v[106:107], 1.0 op_sel_hi:[1,0] neg_lo:[1,0] neg_hi:[1,0]
	v_pk_mul_f32 v[168:169], v[164:165], v[74:75]
	v_pk_mul_f32 v[170:171], v[166:167], v[172:173]
	ds_write_b128 v6, v[168:171]
	ds_read_b128 v[192:195], v7
	ds_read_b128 v[196:199], v7 offset:128
	ds_read_b128 v[200:203], v7 offset:256
	ds_read_b128 v[204:207], v7 offset:384
	ds_read_b128 v[208:211], v7 offset:512
	ds_read_b128 v[212:215], v7 offset:640
	ds_read_b128 v[216:219], v7 offset:768
	v_lshlrev_b32_e32 v108, 16, v58
	v_and_b32_e32 v109, 0xffff0000, v58
	v_lshlrev_b32_e32 v110, 16, v59
	v_and_b32_e32 v111, 0xffff0000, v59
	v_lshlrev_b32_e32 v112, 16, v60
	v_and_b32_e32 v113, 0xffff0000, v60
	v_lshlrev_b32_e32 v114, 16, v61
	v_and_b32_e32 v115, 0xffff0000, v61
	v_lshlrev_b32_e32 v116, 16, v62
	v_and_b32_e32 v117, 0xffff0000, v62
	v_lshlrev_b32_e32 v118, 16, v63
	v_and_b32_e32 v119, 0xffff0000, v63
	v_lshlrev_b32_e32 v120, 16, v64
	v_and_b32_e32 v121, 0xffff0000, v64
	v_lshlrev_b32_e32 v122, 16, v65
	v_and_b32_e32 v123, 0xffff0000, v65
	v_lshlrev_b32_e32 v124, 16, v66
	v_and_b32_e32 v125, 0xffff0000, v66
	v_lshlrev_b32_e32 v126, 16, v67
	v_and_b32_e32 v127, 0xffff0000, v67
	v_lshlrev_b32_e32 v128, 16, v68
	v_and_b32_e32 v129, 0xffff0000, v68
	v_lshlrev_b32_e32 v130, 16, v69
	v_and_b32_e32 v131, 0xffff0000, v69
	v_lshlrev_b32_e32 v132, 16, v70
	v_and_b32_e32 v133, 0xffff0000, v70
	v_lshlrev_b32_e32 v134, 16, v71
	v_and_b32_e32 v135, 0xffff0000, v71
	v_lshlrev_b32_e32 v136, 16, v72
	v_and_b32_e32 v137, 0xffff0000, v72
	v_lshlrev_b32_e32 v138, 16, v73
	v_and_b32_e32 v139, 0xffff0000, v73
	global_load_dwordx2 v[42:43], v3, s[8:9]
	global_load_dwordx2 v[58:59], v2, s[8:9]
	s_add_u32 s8, s8, s10
	s_addc_u32 s9, s9, s11
	global_load_dwordx2 v[44:45], v3, s[8:9]
	global_load_dwordx2 v[60:61], v2, s[8:9]
	s_add_u32 s8, s8, s10
	s_addc_u32 s9, s9, s11
	global_load_dwordx2 v[46:47], v3, s[8:9]
	global_load_dwordx2 v[62:63], v2, s[8:9]
	s_add_u32 s8, s8, s10
	s_addc_u32 s9, s9, s11
	global_load_dwordx2 v[48:49], v3, s[8:9]
	global_load_dwordx2 v[64:65], v2, s[8:9]
	s_add_u32 s8, s8, s10
	s_addc_u32 s9, s9, s11
	global_load_dwordx2 v[50:51], v3, s[8:9]
	global_load_dwordx2 v[66:67], v2, s[8:9]
	s_add_u32 s8, s8, s10
	s_addc_u32 s9, s9, s11
	global_load_dwordx2 v[52:53], v3, s[8:9]
	global_load_dwordx2 v[68:69], v2, s[8:9]
	s_add_u32 s8, s8, s10
	s_addc_u32 s9, s9, s11
	global_load_dwordx2 v[54:55], v3, s[8:9]
	global_load_dwordx2 v[70:71], v2, s[8:9]
	s_add_u32 s8, s8, s10
	s_addc_u32 s9, s9, s11
	global_load_dwordx2 v[56:57], v3, s[8:9]
	global_load_dwordx2 v[72:73], v2, s[8:9]
	s_add_u32 s8, s8, s10
	s_addc_u32 s9, s9, s11
	s_cmp_lt_u32 s16, 63
	s_cselect_b32 s34, s12, s14
	s_cselect_b32 s35, s13, s15
	s_add_u32 s8, s8, s34
	s_addc_u32 s9, s9, s35
	s_add_i32 s16, s16, 1
	v_mov_b32_e32 v176, 1.0
	v_mov_b32_e32 v177, 1.0
	v_mov_b32_e32 v178, 1.0
	v_mov_b32_e32 v179, 1.0
	s_mov_b64 s[34:35], exec
	s_waitcnt lgkmcnt(6)
	s_mov_b64 exec, s[18:19]
	v_pk_mul_f32 v[176:177], v[176:177], v[192:193]
	v_pk_mul_f32 v[178:179], v[178:179], v[194:195]
	s_waitcnt lgkmcnt(5)
	s_mov_b64 exec, s[20:21]
	v_pk_mul_f32 v[176:177], v[176:177], v[196:197]
	v_pk_mul_f32 v[178:179], v[178:179], v[198:199]
	s_waitcnt lgkmcnt(4)
	s_mov_b64 exec, s[22:23]
	v_pk_mul_f32 v[176:177], v[176:177], v[200:201]
	v_pk_mul_f32 v[178:179], v[178:179], v[202:203]
	s_waitcnt lgkmcnt(3)
	s_mov_b64 exec, s[24:25]
	v_pk_mul_f32 v[176:177], v[176:177], v[204:205]
	v_pk_mul_f32 v[178:179], v[178:179], v[206:207]
	s_waitcnt lgkmcnt(2)
	s_mov_b64 exec, s[26:27]
	v_pk_mul_f32 v[176:177], v[176:177], v[208:209]
	v_pk_mul_f32 v[178:179], v[178:179], v[210:211]
	s_waitcnt lgkmcnt(1)
	s_mov_b64 exec, s[28:29]
	v_pk_mul_f32 v[176:177], v[176:177], v[212:213]
	v_pk_mul_f32 v[178:179], v[178:179], v[214:215]
	s_waitcnt lgkmcnt(0)
	s_mov_b64 exec, s[30:31]
	v_pk_mul_f32 v[176:177], v[176:177], v[216:217]
	v_pk_mul_f32 v[178:179], v[178:179], v[218:219]
	s_mov_b64 exec, s[34:35]
	v_pk_mul_f32 v[188:189], v[176:177], v[168:169]
	v_pk_mul_f32 v[190:191], v[178:179], v[170:171]
	s_mov_b64 s[34:35], exec
	s_mov_b64 exec, s[30:31]
	ds_write_b128 v8, v[188:191] offset:512
	s_mov_b64 exec, s[34:35]
	v_max_f32_e32 v180, 0xda24260, v188
	v_max_f32_e32 v181, 0xda24260, v189
	v_max_f32_e32 v182, 0xda24260, v190
	v_max_f32_e32 v183, 0xda24260, v191
	v_rcp_f32_e32 v180, v180
	v_rcp_f32_e32 v181, v181
	v_rcp_f32_e32 v182, v182
	v_rcp_f32_e32 v183, v183
	v_pk_mul_f32 v[192:193], v[136:137], v[188:189]
	v_pk_mul_f32 v[194:195], v[138:139], v[190:191]
	v_pk_mul_f32 v[196:197], v[104:105], v[180:181]
	v_pk_mul_f32 v[198:199], v[106:107], v[182:183]
	v_cvt_pk_bf16_f32 v204, v192, v193
	v_cvt_pk_bf16_f32 v205, v194, v195
	ds_write_b64 v4, v[204:205] offset:20448
	v_cvt_pk_bf16_f32 v206, v196, v197
	v_cvt_pk_bf16_f32 v207, v198, v199
	ds_write_b64 v4, v[206:207] offset:57312
	v_pk_mul_f32 v[180:181], v[180:181], v[74:75]
	v_pk_mul_f32 v[182:183], v[182:183], v[172:173]
	v_pk_mul_f32 v[188:189], v[176:177], v[164:165]
	v_pk_mul_f32 v[190:191], v[178:179], v[166:167]
	v_pk_mul_f32 v[192:193], v[132:133], v[188:189]
	v_pk_mul_f32 v[194:195], v[134:135], v[190:191]
	v_pk_mul_f32 v[200:201], v[100:101], v[180:181]
	v_pk_mul_f32 v[202:203], v[102:103], v[182:183]
	v_cvt_pk_bf16_f32 v204, v192, v193
	v_cvt_pk_bf16_f32 v205, v194, v195
	ds_write_b64 v4, v[204:205] offset:20160
	v_cvt_pk_bf16_f32 v206, v200, v201
	v_cvt_pk_bf16_f32 v207, v202, v203
	ds_write_b64 v4, v[206:207] offset:57024
	v_pk_mul_f32 v[180:181], v[180:181], v[246:247]
	v_pk_mul_f32 v[182:183], v[182:183], v[248:249]
	v_pk_mul_f32 v[188:189], v[176:177], v[160:161]
	v_pk_mul_f32 v[190:191], v[178:179], v[162:163]
	v_pk_mul_f32 v[192:193], v[128:129], v[188:189]
	v_pk_mul_f32 v[194:195], v[130:131], v[190:191]
	v_pk_mul_f32 v[196:197], v[96:97], v[180:181]
	v_pk_mul_f32 v[198:199], v[98:99], v[182:183]
	v_cvt_pk_bf16_f32 v204, v192, v193
	v_cvt_pk_bf16_f32 v205, v194, v195
	ds_write_b64 v4, v[204:205] offset:19872
	v_cvt_pk_bf16_f32 v206, v196, v197
	v_cvt_pk_bf16_f32 v207, v198, v199
	ds_write_b64 v4, v[206:207] offset:56736
	v_pk_mul_f32 v[180:181], v[180:181], v[242:243]
	v_pk_mul_f32 v[182:183], v[182:183], v[244:245]
	v_pk_mul_f32 v[188:189], v[176:177], v[156:157]
	v_pk_mul_f32 v[190:191], v[178:179], v[158:159]
	v_pk_mul_f32 v[192:193], v[124:125], v[188:189]
	v_pk_mul_f32 v[194:195], v[126:127], v[190:191]
	v_pk_mul_f32 v[200:201], v[92:93], v[180:181]
	v_pk_mul_f32 v[202:203], v[94:95], v[182:183]
	v_cvt_pk_bf16_f32 v204, v192, v193
	v_cvt_pk_bf16_f32 v205, v194, v195
	ds_write_b64 v4, v[204:205] offset:19584
	v_cvt_pk_bf16_f32 v206, v200, v201
	v_cvt_pk_bf16_f32 v207, v202, v203
	ds_write_b64 v4, v[206:207] offset:56448
	v_pk_mul_f32 v[180:181], v[180:181], v[238:239]
	v_pk_mul_f32 v[182:183], v[182:183], v[240:241]
	v_pk_mul_f32 v[188:189], v[176:177], v[152:153]
	v_pk_mul_f32 v[190:191], v[178:179], v[154:155]
	v_pk_mul_f32 v[192:193], v[120:121], v[188:189]
	v_pk_mul_f32 v[194:195], v[122:123], v[190:191]
	v_pk_mul_f32 v[196:197], v[88:89], v[180:181]
	v_pk_mul_f32 v[198:199], v[90:91], v[182:183]
	v_cvt_pk_bf16_f32 v204, v192, v193
	v_cvt_pk_bf16_f32 v205, v194, v195
	ds_write_b64 v4, v[204:205] offset:19296
	v_cvt_pk_bf16_f32 v206, v196, v197
	v_cvt_pk_bf16_f32 v207, v198, v199
	ds_write_b64 v4, v[206:207] offset:56160
	v_pk_mul_f32 v[180:181], v[180:181], v[234:235]
	v_pk_mul_f32 v[182:183], v[182:183], v[236:237]
	v_pk_mul_f32 v[188:189], v[176:177], v[148:149]
	v_pk_mul_f32 v[190:191], v[178:179], v[150:151]
	v_pk_mul_f32 v[192:193], v[116:117], v[188:189]
	v_pk_mul_f32 v[194:195], v[118:119], v[190:191]
	v_pk_mul_f32 v[200:201], v[84:85], v[180:181]
	v_pk_mul_f32 v[202:203], v[86:87], v[182:183]
	v_cvt_pk_bf16_f32 v204, v192, v193
	v_cvt_pk_bf16_f32 v205, v194, v195
	ds_write_b64 v4, v[204:205] offset:19008
	v_cvt_pk_bf16_f32 v206, v200, v201
	v_cvt_pk_bf16_f32 v207, v202, v203
	ds_write_b64 v4, v[206:207] offset:55872
	v_pk_mul_f32 v[180:181], v[180:181], v[230:231]
	v_pk_mul_f32 v[182:183], v[182:183], v[232:233]
	v_pk_mul_f32 v[188:189], v[176:177], v[144:145]
	v_pk_mul_f32 v[190:191], v[178:179], v[146:147]
	v_pk_mul_f32 v[192:193], v[112:113], v[188:189]
	v_pk_mul_f32 v[194:195], v[114:115], v[190:191]
	v_pk_mul_f32 v[196:197], v[80:81], v[180:181]
	v_pk_mul_f32 v[198:199], v[82:83], v[182:183]
	v_cvt_pk_bf16_f32 v204, v192, v193
	v_cvt_pk_bf16_f32 v205, v194, v195
	ds_write_b64 v4, v[204:205] offset:18720
	v_cvt_pk_bf16_f32 v206, v196, v197
	v_cvt_pk_bf16_f32 v207, v198, v199
	ds_write_b64 v4, v[206:207] offset:55584
	v_pk_mul_f32 v[180:181], v[180:181], v[226:227]
	v_pk_mul_f32 v[182:183], v[182:183], v[228:229]
	v_pk_mul_f32 v[188:189], v[176:177], v[140:141]
	v_pk_mul_f32 v[190:191], v[178:179], v[142:143]
	v_pk_mul_f32 v[192:193], v[108:109], v[188:189]
	v_pk_mul_f32 v[194:195], v[110:111], v[190:191]
	v_pk_mul_f32 v[200:201], v[76:77], v[180:181]
	v_pk_mul_f32 v[202:203], v[78:79], v[182:183]
	v_cvt_pk_bf16_f32 v204, v192, v193
	v_cvt_pk_bf16_f32 v205, v194, v195
	ds_write_b64 v4, v[204:205] offset:18432
	v_cvt_pk_bf16_f32 v206, v200, v201
	v_cvt_pk_bf16_f32 v207, v202, v203
	ds_write_b64 v4, v[206:207] offset:55296
	s_waitcnt lgkmcnt(0)
	s_barrier
	s_cmp_eq_u32 s17, 0
	s_cbranch_scc1 .Lhg_pend
	s_waitcnt vmcnt(16)
	v_lshlrev_b32_e32 v76, 16, v10
	v_and_b32_e32 v77, 0xffff0000, v10
	v_lshlrev_b32_e32 v78, 16, v11
	v_and_b32_e32 v79, 0xffff0000, v11
	v_lshlrev_b32_e32 v80, 16, v12
	v_and_b32_e32 v81, 0xffff0000, v12
	v_lshlrev_b32_e32 v82, 16, v13
	v_and_b32_e32 v83, 0xffff0000, v13
	v_lshlrev_b32_e32 v84, 16, v14
	v_and_b32_e32 v85, 0xffff0000, v14
	v_lshlrev_b32_e32 v86, 16, v15
	v_and_b32_e32 v87, 0xffff0000, v15
	v_lshlrev_b32_e32 v88, 16, v16
	v_and_b32_e32 v89, 0xffff0000, v16
	v_lshlrev_b32_e32 v90, 16, v17
	v_and_b32_e32 v91, 0xffff0000, v17
	v_lshlrev_b32_e32 v92, 16, v18
	v_and_b32_e32 v93, 0xffff0000, v18
	v_lshlrev_b32_e32 v94, 16, v19
	v_and_b32_e32 v95, 0xffff0000, v19
	v_lshlrev_b32_e32 v96, 16, v20
	v_and_b32_e32 v97, 0xffff0000, v20
	v_lshlrev_b32_e32 v98, 16, v21
	v_and_b32_e32 v99, 0xffff0000, v21
	v_lshlrev_b32_e32 v100, 16, v22
	v_and_b32_e32 v101, 0xffff0000, v22
	v_lshlrev_b32_e32 v102, 16, v23
	v_and_b32_e32 v103, 0xffff0000, v23
	v_lshlrev_b32_e32 v104, 16, v24
	v_and_b32_e32 v105, 0xffff0000, v24
	v_lshlrev_b32_e32 v106, 16, v25
	v_and_b32_e32 v107, 0xffff0000, v25
	v_pk_add_f32 v[140:141], v[76:77], 1.0 op_sel_hi:[1,0] neg_lo:[1,0] neg_hi:[1,0]
	v_pk_add_f32 v[142:143], v[78:79], 1.0 op_sel_hi:[1,0] neg_lo:[1,0] neg_hi:[1,0]
	v_pk_add_f32 v[226:227], v[80:81], 1.0 op_sel_hi:[1,0] neg_lo:[1,0] neg_hi:[1,0]
	v_pk_add_f32 v[228:229], v[82:83], 1.0 op_sel_hi:[1,0] neg_lo:[1,0] neg_hi:[1,0]
	v_pk_mul_f32 v[144:145], v[140:141], v[226:227]
	v_pk_mul_f32 v[146:147], v[142:143], v[228:229]
	v_pk_add_f32 v[230:231], v[84:85], 1.0 op_sel_hi:[1,0] neg_lo:[1,0] neg_hi:[1,0]
	v_pk_add_f32 v[232:233], v[86:87], 1.0 op_sel_hi:[1,0] neg_lo:[1,0] neg_hi:[1,0]
	v_pk_mul_f32 v[148:149], v[144:145], v[230:231]
	v_pk_mul_f32 v[150:151], v[146:147], v[232:233]
	v_pk_add_f32 v[234:235], v[88:89], 1.0 op_sel_hi:[1,0] neg_lo:[1,0] neg_hi:[1,0]
	v_pk_add_f32 v[236:237], v[90:91], 1.0 op_sel_hi:[1,0] neg_lo:[1,0] neg_hi:[1,0]
	v_pk_mul_f32 v[152:153], v[148:149], v[234:235]
	v_pk_mul_f32 v[154:155], v[150:151], v[236:237]
	v_pk_add_f32 v[238:239], v[92:93], 1.0 op_sel_hi:[1,0] neg_lo:[1,0] neg_hi:[1,0]
	v_pk_add_f32 v[240:241], v[94:95], 1.0 op_sel_hi:[1,0] neg_lo:[1,0] neg_hi:[1,0]
	v_pk_mul_f32 v[156:157], v[152:153], v[238:239]
	v_pk_mul_f32 v[158:159], v[154:155], v[240:241]
	v_pk_add_f32 v[242:243], v[96:97], 1.0 op_sel_hi:[1,0] neg_lo:[1,0] neg_hi:[1,0]
	v_pk_add_f32 v[244:245], v[98:99], 1.0 op_sel_hi:[1,0] neg_lo:[1,0] neg_hi:[1,0]
	v_pk_mul_f32 v[160:161], v[156:157], v[242:243]
	v_pk_mul_f32 v[162:163], v[158:159], v[244:245]
	v_pk_add_f32 v[246:247], v[100:101], 1.0 op_sel_hi:[1,0] neg_lo:[1,0] neg_hi:[1,0]
	v_pk_add_f32 v[248:249], v[102:103], 1.0 op_sel_hi:[1,0] neg_lo:[1,0] neg_hi:[1,0]
	v_pk_mul_f32 v[164:165], v[160:161], v[246:247]
	v_pk_mul_f32 v[166:167], v[162:163], v[248:249]
	v_pk_add_f32 v[74:75], v[104:105], 1.0 op_sel_hi:[1,0] neg_lo:[1,0] neg_hi:[1,0]
	v_pk_add_f32 v[172:173], v[106:107], 1.0 op_sel_hi:[1,0] neg_lo:[1,0] neg_hi:[1,0]
	v_pk_mul_f32 v[168:169], v[164:165], v[74:75]
	v_pk_mul_f32 v[170:171], v[166:167], v[172:173]
	ds_write_b128 v6, v[168:171]
	ds_read_b128 v[192:195], v7
	ds_read_b128 v[196:199], v7 offset:128
	ds_read_b128 v[200:203], v7 offset:256
	ds_read_b128 v[204:207], v7 offset:384
	ds_read_b128 v[208:211], v7 offset:512
	ds_read_b128 v[212:215], v7 offset:640
	ds_read_b128 v[216:219], v7 offset:768
	v_lshlrev_b32_e32 v108, 16, v26
	v_and_b32_e32 v109, 0xffff0000, v26
	v_lshlrev_b32_e32 v110, 16, v27
	v_and_b32_e32 v111, 0xffff0000, v27
	v_lshlrev_b32_e32 v112, 16, v28
	v_and_b32_e32 v113, 0xffff0000, v28
	v_lshlrev_b32_e32 v114, 16, v29
	v_and_b32_e32 v115, 0xffff0000, v29
	v_lshlrev_b32_e32 v116, 16, v30
	v_and_b32_e32 v117, 0xffff0000, v30
	v_lshlrev_b32_e32 v118, 16, v31
	v_and_b32_e32 v119, 0xffff0000, v31
	v_lshlrev_b32_e32 v120, 16, v32
	v_and_b32_e32 v121, 0xffff0000, v32
	v_lshlrev_b32_e32 v122, 16, v33
	v_and_b32_e32 v123, 0xffff0000, v33
	v_lshlrev_b32_e32 v124, 16, v34
	v_and_b32_e32 v125, 0xffff0000, v34
	v_lshlrev_b32_e32 v126, 16, v35
	v_and_b32_e32 v127, 0xffff0000, v35
	v_lshlrev_b32_e32 v128, 16, v36
	v_and_b32_e32 v129, 0xffff0000, v36
	v_lshlrev_b32_e32 v130, 16, v37
	v_and_b32_e32 v131, 0xffff0000, v37
	v_lshlrev_b32_e32 v132, 16, v38
	v_and_b32_e32 v133, 0xffff0000, v38
	v_lshlrev_b32_e32 v134, 16, v39
	v_and_b32_e32 v135, 0xffff0000, v39
	v_lshlrev_b32_e32 v136, 16, v40
	v_and_b32_e32 v137, 0xffff0000, v40
	v_lshlrev_b32_e32 v138, 16, v41
	v_and_b32_e32 v139, 0xffff0000, v41
	global_load_dwordx2 v[10:11], v3, s[8:9]
	global_load_dwordx2 v[26:27], v2, s[8:9]
	s_add_u32 s8, s8, s10
	s_addc_u32 s9, s9, s11
	global_load_dwordx2 v[12:13], v3, s[8:9]
	global_load_dwordx2 v[28:29], v2, s[8:9]
	s_add_u32 s8, s8, s10
	s_addc_u32 s9, s9, s11
	global_load_dwordx2 v[14:15], v3, s[8:9]
	global_load_dwordx2 v[30:31], v2, s[8:9]
	s_add_u32 s8, s8, s10
	s_addc_u32 s9, s9, s11
	global_load_dwordx2 v[16:17], v3, s[8:9]
	global_load_dwordx2 v[32:33], v2, s[8:9]
	s_add_u32 s8, s8, s10
	s_addc_u32 s9, s9, s11
	global_load_dwordx2 v[18:19], v3, s[8:9]
	global_load_dwordx2 v[34:35], v2, s[8:9]
	s_add_u32 s8, s8, s10
	s_addc_u32 s9, s9, s11
	global_load_dwordx2 v[20:21], v3, s[8:9]
	global_load_dwordx2 v[36:37], v2, s[8:9]
	s_add_u32 s8, s8, s10
	s_addc_u32 s9, s9, s11
	global_load_dwordx2 v[22:23], v3, s[8:9]
	global_load_dwordx2 v[38:39], v2, s[8:9]
	s_add_u32 s8, s8, s10
	s_addc_u32 s9, s9, s11
	global_load_dwordx2 v[24:25], v3, s[8:9]
	global_load_dwordx2 v[40:41], v2, s[8:9]
	s_add_u32 s8, s8, s10
	s_addc_u32 s9, s9, s11
	s_cmp_lt_u32 s16, 63
	s_cselect_b32 s34, s12, s14
	s_cselect_b32 s35, s13, s15
	s_add_u32 s8, s8, s34
	s_addc_u32 s9, s9, s35
	s_add_i32 s16, s16, 1
	v_mov_b32_e32 v176, 1.0
	v_mov_b32_e32 v177, 1.0
	v_mov_b32_e32 v178, 1.0
	v_mov_b32_e32 v179, 1.0
	s_mov_b64 s[34:35], exec
	s_waitcnt lgkmcnt(6)
	s_mov_b64 exec, s[18:19]
	v_pk_mul_f32 v[176:177], v[176:177], v[192:193]
	v_pk_mul_f32 v[178:179], v[178:179], v[194:195]
	s_waitcnt lgkmcnt(5)
	s_mov_b64 exec, s[20:21]
	v_pk_mul_f32 v[176:177], v[176:177], v[196:197]
	v_pk_mul_f32 v[178:179], v[178:179], v[198:199]
	s_waitcnt lgkmcnt(4)
	s_mov_b64 exec, s[22:23]
	v_pk_mul_f32 v[176:177], v[176:177], v[200:201]
	v_pk_mul_f32 v[178:179], v[178:179], v[202:203]
	s_waitcnt lgkmcnt(3)
	s_mov_b64 exec, s[24:25]
	v_pk_mul_f32 v[176:177], v[176:177], v[204:205]
	v_pk_mul_f32 v[178:179], v[178:179], v[206:207]
	s_waitcnt lgkmcnt(2)
	s_mov_b64 exec, s[26:27]
	v_pk_mul_f32 v[176:177], v[176:177], v[208:209]
	v_pk_mul_f32 v[178:179], v[178:179], v[210:211]
	s_waitcnt lgkmcnt(1)
	s_mov_b64 exec, s[28:29]
	v_pk_mul_f32 v[176:177], v[176:177], v[212:213]
	v_pk_mul_f32 v[178:179], v[178:179], v[214:215]
	s_waitcnt lgkmcnt(0)
	s_mov_b64 exec, s[30:31]
	v_pk_mul_f32 v[176:177], v[176:177], v[216:217]
	v_pk_mul_f32 v[178:179], v[178:179], v[218:219]
	s_mov_b64 exec, s[34:35]
	v_pk_mul_f32 v[188:189], v[176:177], v[168:169]
	v_pk_mul_f32 v[190:191], v[178:179], v[170:171]
	s_mov_b64 s[34:35], exec
	s_mov_b64 exec, s[30:31]
	ds_write_b128 v8, v[188:191]
	s_mov_b64 exec, s[34:35]
	v_max_f32_e32 v180, 0xda24260, v188
	v_max_f32_e32 v181, 0xda24260, v189
	v_max_f32_e32 v182, 0xda24260, v190
	v_max_f32_e32 v183, 0xda24260, v191
	v_rcp_f32_e32 v180, v180
	v_rcp_f32_e32 v181, v181
	v_rcp_f32_e32 v182, v182
	v_rcp_f32_e32 v183, v183
	v_pk_mul_f32 v[192:193], v[136:137], v[188:189]
	v_pk_mul_f32 v[194:195], v[138:139], v[190:191]
	v_pk_mul_f32 v[196:197], v[104:105], v[180:181]
	v_pk_mul_f32 v[198:199], v[106:107], v[182:183]
	v_cvt_pk_bf16_f32 v204, v192, v193
	v_cvt_pk_bf16_f32 v205, v194, v195
	ds_write_b64 v4, v[204:205] offset:2016
	v_cvt_pk_bf16_f32 v206, v196, v197
	v_cvt_pk_bf16_f32 v207, v198, v199
	ds_write_b64 v4, v[206:207] offset:38880
	v_pk_mul_f32 v[180:181], v[180:181], v[74:75]
	v_pk_mul_f32 v[182:183], v[182:183], v[172:173]
	v_pk_mul_f32 v[188:189], v[176:177], v[164:165]
	v_pk_mul_f32 v[190:191], v[178:179], v[166:167]
	v_pk_mul_f32 v[192:193], v[132:133], v[188:189]
	v_pk_mul_f32 v[194:195], v[134:135], v[190:191]
	v_pk_mul_f32 v[200:201], v[100:101], v[180:181]
	v_pk_mul_f32 v[202:203], v[102:103], v[182:183]
	v_cvt_pk_bf16_f32 v204, v192, v193
	v_cvt_pk_bf16_f32 v205, v194, v195
	ds_write_b64 v4, v[204:205] offset:1728
	v_cvt_pk_bf16_f32 v206, v200, v201
	v_cvt_pk_bf16_f32 v207, v202, v203
	ds_write_b64 v4, v[206:207] offset:38592
	v_pk_mul_f32 v[180:181], v[180:181], v[246:247]
	v_pk_mul_f32 v[182:183], v[182:183], v[248:249]
	v_pk_mul_f32 v[188:189], v[176:177], v[160:161]
	v_pk_mul_f32 v[190:191], v[178:179], v[162:163]
	v_pk_mul_f32 v[192:193], v[128:129], v[188:189]
	v_pk_mul_f32 v[194:195], v[130:131], v[190:191]
	v_pk_mul_f32 v[196:197], v[96:97], v[180:181]
	v_pk_mul_f32 v[198:199], v[98:99], v[182:183]
	v_cvt_pk_bf16_f32 v204, v192, v193
	v_cvt_pk_bf16_f32 v205, v194, v195
	ds_write_b64 v4, v[204:205] offset:1440
	v_cvt_pk_bf16_f32 v206, v196, v197
	v_cvt_pk_bf16_f32 v207, v198, v199
	ds_write_b64 v4, v[206:207] offset:38304
	v_pk_mul_f32 v[180:181], v[180:181], v[242:243]
	v_pk_mul_f32 v[182:183], v[182:183], v[244:245]
	v_pk_mul_f32 v[188:189], v[176:177], v[156:157]
	v_pk_mul_f32 v[190:191], v[178:179], v[158:159]
	v_pk_mul_f32 v[192:193], v[124:125], v[188:189]
	v_pk_mul_f32 v[194:195], v[126:127], v[190:191]
	v_pk_mul_f32 v[200:201], v[92:93], v[180:181]
	v_pk_mul_f32 v[202:203], v[94:95], v[182:183]
	v_cvt_pk_bf16_f32 v204, v192, v193
	v_cvt_pk_bf16_f32 v205, v194, v195
	ds_write_b64 v4, v[204:205] offset:1152
	v_cvt_pk_bf16_f32 v206, v200, v201
	v_cvt_pk_bf16_f32 v207, v202, v203
	ds_write_b64 v4, v[206:207] offset:38016
	v_pk_mul_f32 v[180:181], v[180:181], v[238:239]
	v_pk_mul_f32 v[182:183], v[182:183], v[240:241]
	v_pk_mul_f32 v[188:189], v[176:177], v[152:153]
	v_pk_mul_f32 v[190:191], v[178:179], v[154:155]
	v_pk_mul_f32 v[192:193], v[120:121], v[188:189]
	v_pk_mul_f32 v[194:195], v[122:123], v[190:191]
	v_pk_mul_f32 v[196:197], v[88:89], v[180:181]
	v_pk_mul_f32 v[198:199], v[90:91], v[182:183]
	v_cvt_pk_bf16_f32 v204, v192, v193
	v_cvt_pk_bf16_f32 v205, v194, v195
	ds_write_b64 v4, v[204:205] offset:864
	v_cvt_pk_bf16_f32 v206, v196, v197
	v_cvt_pk_bf16_f32 v207, v198, v199
	ds_write_b64 v4, v[206:207] offset:37728
	v_pk_mul_f32 v[180:181], v[180:181], v[234:235]
	v_pk_mul_f32 v[182:183], v[182:183], v[236:237]
	v_pk_mul_f32 v[188:189], v[176:177], v[148:149]
	v_pk_mul_f32 v[190:191], v[178:179], v[150:151]
	v_pk_mul_f32 v[192:193], v[116:117], v[188:189]
	v_pk_mul_f32 v[194:195], v[118:119], v[190:191]
	v_pk_mul_f32 v[200:201], v[84:85], v[180:181]
	v_pk_mul_f32 v[202:203], v[86:87], v[182:183]
	v_cvt_pk_bf16_f32 v204, v192, v193
	v_cvt_pk_bf16_f32 v205, v194, v195
	ds_write_b64 v4, v[204:205] offset:576
	v_cvt_pk_bf16_f32 v206, v200, v201
	v_cvt_pk_bf16_f32 v207, v202, v203
	ds_write_b64 v4, v[206:207] offset:37440
	v_pk_mul_f32 v[180:181], v[180:181], v[230:231]
	v_pk_mul_f32 v[182:183], v[182:183], v[232:233]
	v_pk_mul_f32 v[188:189], v[176:177], v[144:145]
	v_pk_mul_f32 v[190:191], v[178:179], v[146:147]
	v_pk_mul_f32 v[192:193], v[112:113], v[188:189]
	v_pk_mul_f32 v[194:195], v[114:115], v[190:191]
	v_pk_mul_f32 v[196:197], v[80:81], v[180:181]
	v_pk_mul_f32 v[198:199], v[82:83], v[182:183]
	v_cvt_pk_bf16_f32 v204, v192, v193
	v_cvt_pk_bf16_f32 v205, v194, v195
	ds_write_b64 v4, v[204:205] offset:288
	v_cvt_pk_bf16_f32 v206, v196, v197
	v_cvt_pk_bf16_f32 v207, v198, v199
	ds_write_b64 v4, v[206:207] offset:37152
	v_pk_mul_f32 v[180:181], v[180:181], v[226:227]
	v_pk_mul_f32 v[182:183], v[182:183], v[228:229]
	v_pk_mul_f32 v[188:189], v[176:177], v[140:141]
	v_pk_mul_f32 v[190:191], v[178:179], v[142:143]
	v_pk_mul_f32 v[192:193], v[108:109], v[188:189]
	v_pk_mul_f32 v[194:195], v[110:111], v[190:191]
	v_pk_mul_f32 v[200:201], v[76:77], v[180:181]
	v_pk_mul_f32 v[202:203], v[78:79], v[182:183]
	v_cvt_pk_bf16_f32 v204, v192, v193
	v_cvt_pk_bf16_f32 v205, v194, v195
	ds_write_b64 v4, v[204:205]
	v_cvt_pk_bf16_f32 v206, v200, v201
	v_cvt_pk_bf16_f32 v207, v202, v203
	ds_write_b64 v4, v[206:207] offset:36864
	s_waitcnt lgkmcnt(0)
	s_barrier
	s_add_i32 s17, s17, -1
	s_branch .Lhg_ploop

.Lhg_sinit:
	s_sub_i32 s7, s6, 4
	v_and_b32_e32 v20, 15, v1
	v_lshrrev_b32_e32 v21, 4, v1
	s_lshl_b32 s28, s7, 4
	v_add_u32_e32 v22, s28, v20
	v_mul_u32_u24_e32 v2, 0x120, v22
	v_lshl_add_u32 v2, v21, 4, v2
	v_mul_u32_u24_e32 v3, 0x120, v20
	v_lshl_add_u32 v3, v21, 4, v3
	v_add_u32_e32 v6, 0x1e800, v3
	v_add_u32_e32 v3, 0x9000, v3
	v_mul_u32_u24_e32 v23, 0xa0, v20
	v_lshl_add_u32 v4, v21, 3, v23
	v_add_u32_e32 v4, 0x1c000, v4
	v_lshl_add_u32 v5, v21, 4, v23
	v_add_u32_e32 v5, 0x1c000, v5
	v_mul_u32_u24_e32 v7, 0x120, v20
	v_lshl_add_u32 v7, v21, 3, v7
	s_lshl_b32 s29, s7, 6
	v_add_u32_e32 v7, s29, v7
	v_add_u32_e32 v7, 0x1e800, v7
	v_lshrrev_b32_e32 v24, 2, v20
	v_lshl_add_u32 v24, v21, 3, v24
	v_mul_u32_u24_e32 v24, 0x120, v24
	v_and_b32_e32 v25, 3, v20
	v_lshl_add_u32 v24, v25, 3, v24
	s_lshl_b32 s29, s7, 6
	v_add_u32_e32 v24, s29, v24
	v_add_u32_e32 v8, 0x9000, v24
	s_lshl_b32 s29, s7, 7
	v_lshl_add_u32 v12, v21, 4, s29
	v_add_u32_e32 v12, 0x24000, v12
	v_sub_u32_e32 v24, 0xfff, v22
	s_mov_b64 vcc, s[36:37]
	v_cndmask_b32_e32 v24, v24, v22, vcc
	s_lshl_b32 s29, s5, 14
	s_lshl_b32 s30, s4, 12
	s_add_i32 s29, s29, s30
	v_add_u32_e32 v24, s29, v24
	v_lshlrev_b32_e32 v24, 10, v24
	s_lshl_b32 s29, s3, 8
	s_lshl_b32 s30, s2, 6
	s_add_i32 s29, s29, s30
	v_lshl_add_u32 v25, v21, 3, s29
	v_add_u32_e32 v24, v24, v25
	v_mov_b32_e32 v25, 0
	v_readlane_b32 s30, v250, 12
	v_readlane_b32 s31, v250, 13
	s_nop 1
	v_lshl_add_u64 v[14:15], s[30:31], 0, v[24:25]
	s_lshl_b32 s29, s5, 1
	s_sub_i32 s29, 1, s29
	s_mul_i32 s26, s29, 0x10000
	s_ashr_i32 s27, s26, 31
	s_mul_i32 s10, s29, 0x98000
	s_ashr_i32 s11, s10, 31
	s_lshl_b32 s29, s7, 6
	v_add_u32_e32 v24, s29, v1
	v_lshrrev_b32_e32 v25, 2, v24
	v_and_b32_e32 v26, 3, v24
	v_mul_u32_u24_e32 v16, 0x2600, v25
	v_lshl_add_u32 v16, v26, 4, v16
	s_lshl_b32 s29, s4, 12
	s_mul_i32 s30, s5, 0xfc0
	s_add_i32 s29, s29, s30
	s_mul_i32 s29, s29, 0x2600
	s_lshl_b32 s30, s3, 8
	s_add_i32 s29, s29, s30
	s_lshl_b32 s30, s2, 6
	s_add_i32 s29, s29, s30
	s_add_i32 s29, s29, 0x101e00
	s_add_u32 s8, s98, s29
	s_addc_u32 s9, s99, 0
	s_mov_b32 s16, 0
	v_sub_u32_e32 v27, 63, v25
	s_mov_b64 vcc, s[36:37]
	v_cndmask_b32_e32 v27, v27, v25, vcc
	v_mul_u32_u24_e32 v17, 0x500, v26
	v_lshl_add_u32 v17, v27, 1, v17
	v_add_u32_e32 v17, 0x1c000, v17
	v_lshlrev_b32_e32 v24, 2, v21
	v_cmp_le_u32_e64 s[18:19], v24, v20
	v_add_u32_e32 v25, 1, v24
	v_cmp_le_u32_e64 s[20:21], v25, v20
	v_add_u32_e32 v25, 2, v24
	v_cmp_le_u32_e64 s[22:23], v25, v20
	v_add_u32_e32 v25, 3, v24
	v_cmp_le_u32_e64 s[24:25], v25, v20
	v_mov_b32_e32 v200, 0
	v_mov_b32_e32 v201, 0
	v_mov_b32_e32 v202, 0
	v_mov_b32_e32 v203, 0
	v_mov_b32_e32 v204, 0
	v_mov_b32_e32 v205, 0
	v_mov_b32_e32 v206, 0
	v_mov_b32_e32 v207, 0
	v_mov_b32_e32 v208, 0
	v_mov_b32_e32 v209, 0
	v_mov_b32_e32 v210, 0
	v_mov_b32_e32 v211, 0
	v_mov_b32_e32 v212, 0
	v_mov_b32_e32 v213, 0
	v_mov_b32_e32 v214, 0
	v_mov_b32_e32 v215, 0
	v_mov_b32_e32 v92, 0
	v_mov_b32_e32 v93, 0
	v_mov_b32_e32 v94, 0
	v_mov_b32_e32 v95, 0
	v_mov_b32_e32 v96, 0
	v_mov_b32_e32 v97, 0
	v_mov_b32_e32 v98, 0
	v_mov_b32_e32 v99, 0
	global_load_dwordx4 v[18:21], v16, s[8:9]
	s_cmp_lt_u32 s16, 63
	s_cselect_b32 s34, s10, 0
	s_cselect_b32 s35, s11, 0
	s_add_u32 s8, s8, s34
	s_addc_u32 s9, s9, s35
	s_add_i32 s16, s16, 1
	global_load_dwordx4 v[22:25], v16, s[8:9]
	s_cmp_lt_u32 s16, 63
	s_cselect_b32 s34, s10, 0
	s_cselect_b32 s35, s11, 0
	s_add_u32 s8, s8, s34
	s_addc_u32 s9, s9, s35
	s_add_i32 s16, s16, 1
	s_waitcnt vmcnt(0)
	s_waitcnt lgkmcnt(0)
	s_barrier
	s_mov_b64 s[38:39], exec
	v_readlane_b32 s40, v250, 10
	v_readlane_b32 s41, v250, 11
	s_and_b64 s[40:41], s[38:39], s[40:41]
	s_mov_b64 exec, s[40:41]
	s_cbranch_execz .Lhg_rel1
	s_mov_b64 s[40:41], exec
	v_mbcnt_lo_u32_b32 v224, s40, 0
	buffer_wbl2 sc1
	s_waitcnt vmcnt(0)
	v_mbcnt_hi_u32_b32 v224, s41, v224
	v_cmp_eq_u32_e32 vcc, 0, v224
	s_and_b64 s[42:43], exec, vcc
	s_mov_b64 exec, s[42:43]
	s_cbranch_execz .Lhg_rel1
	s_bcnt1_i32_b64 s42, s[40:41]
	s_lshl_b32 s40, s1, 7
	s_add_u32 s40, s98, s40
	s_addc_u32 s41, s99, 0
	v_mov_b32_e32 v224, 0x2000
	v_mov_b32_e32 v225, s42
	global_atomic_add v224, v225, s[40:41]

.Lhg_sloop:
	s_waitcnt vmcnt(3)
	ds_write_b16 v17, v22 offset:5120
	ds_write_b16_d16_hi v17, v22 offset:5280
	ds_write_b16 v17, v23 offset:5440
	ds_write_b16_d16_hi v17, v23 offset:5600
	ds_write_b16 v17, v24 offset:5760
	ds_write_b16_d16_hi v17, v24 offset:5920
	ds_write_b16 v17, v25 offset:6080
	ds_write_b16_d16_hi v17, v25 offset:6240
	ds_read_b128 v[28:31], v2
	ds_read_b128 v[32:35], v2 offset:64
	ds_read_b128 v[36:39], v2 offset:128
	ds_read_b128 v[40:43], v2 offset:192
	ds_read_b128 v[44:47], v3
	ds_read_b128 v[48:51], v3 offset:64
	ds_read_b128 v[52:55], v3 offset:128
	ds_read_b128 v[56:59], v3 offset:192
	s_cmp_eq_u32 s7, 0
	s_cbranch_scc1 .Lhg_lt0_0
	ds_read_b128 v[60:63], v3 offset:4608
	ds_read_b128 v[64:67], v3 offset:4672
	ds_read_b128 v[68:71], v3 offset:4736
	ds_read_b128 v[72:75], v3 offset:4800
	s_waitcnt lgkmcnt(7)
	v_mfma_f32_16x16x32_bf16 v[76:79], v[44:47], v[28:31], 0
	s_waitcnt lgkmcnt(6)
	v_mfma_f32_16x16x32_bf16 v[76:79], v[48:51], v[32:35], v[76:79]
	s_waitcnt lgkmcnt(5)
	v_mfma_f32_16x16x32_bf16 v[76:79], v[52:55], v[36:39], v[76:79]
	s_waitcnt lgkmcnt(4)
	v_mfma_f32_16x16x32_bf16 v[76:79], v[56:59], v[40:43], v[76:79]
	s_cmp_eq_u32 s7, 1
	s_cbranch_scc1 .Lhg_lt0_1
	ds_read_b128 v[44:47], v3 offset:9216
	ds_read_b128 v[48:51], v3 offset:9280
	ds_read_b128 v[52:55], v3 offset:9344
	ds_read_b128 v[56:59], v3 offset:9408
	s_waitcnt lgkmcnt(7)
	v_mfma_f32_16x16x32_bf16 v[80:83], v[60:63], v[28:31], 0
	s_waitcnt lgkmcnt(6)
	v_mfma_f32_16x16x32_bf16 v[80:83], v[64:67], v[32:35], v[80:83]
	s_waitcnt lgkmcnt(5)
	v_mfma_f32_16x16x32_bf16 v[80:83], v[68:71], v[36:39], v[80:83]
	s_waitcnt lgkmcnt(4)
	v_mfma_f32_16x16x32_bf16 v[80:83], v[72:75], v[40:43], v[80:83]
	s_cmp_eq_u32 s7, 2
	s_cbranch_scc1 .Lhg_lt0_2
	ds_read_b128 v[60:63], v3 offset:13824
	ds_read_b128 v[64:67], v3 offset:13888
	ds_read_b128 v[68:71], v3 offset:13952
	ds_read_b128 v[72:75], v3 offset:14016
	s_waitcnt lgkmcnt(7)
	v_mfma_f32_16x16x32_bf16 v[84:87], v[44:47], v[28:31], 0
	s_waitcnt lgkmcnt(6)
	v_mfma_f32_16x16x32_bf16 v[84:87], v[48:51], v[32:35], v[84:87]
	s_waitcnt lgkmcnt(5)
	v_mfma_f32_16x16x32_bf16 v[84:87], v[52:55], v[36:39], v[84:87]
	s_waitcnt lgkmcnt(4)
	v_mfma_f32_16x16x32_bf16 v[84:87], v[56:59], v[40:43], v[84:87]
	ds_read_b64 v[100:101], v4
	ds_read_b64 v[102:103], v4 offset:32
	ds_read_b64 v[104:105], v4 offset:64
	ds_read_b64 v[106:107], v4 offset:96
	ds_read_b64 v[108:109], v4 offset:2560
	ds_read_b64 v[110:111], v4 offset:2592
	ds_read_b64 v[112:113], v4 offset:2624
	ds_read_b64 v[114:115], v4 offset:2656
	ds_read_b128 v[124:127], v6
	ds_read_b128 v[128:131], v6 offset:64
	ds_read_b128 v[132:135], v6 offset:128
	ds_read_b128 v[136:139], v6 offset:192
	s_waitcnt lgkmcnt(15)
	v_mfma_f32_16x16x32_bf16 v[88:91], v[60:63], v[28:31], 0
	s_waitcnt lgkmcnt(14)
	v_mfma_f32_16x16x32_bf16 v[88:91], v[64:67], v[32:35], v[88:91]
	s_waitcnt lgkmcnt(13)
	v_mfma_f32_16x16x32_bf16 v[88:91], v[68:71], v[36:39], v[88:91]
	s_waitcnt lgkmcnt(12)
	v_mfma_f32_16x16x32_bf16 v[88:91], v[72:75], v[40:43], v[88:91]
	s_branch .Lhg_sc0
.Lhg_lt0_0:
	ds_read_b64 v[100:101], v4
	ds_read_b64 v[102:103], v4 offset:32
	ds_read_b64 v[104:105], v4 offset:64
	ds_read_b64 v[106:107], v4 offset:96
	ds_read_b64 v[108:109], v4 offset:2560
	ds_read_b64 v[110:111], v4 offset:2592
	ds_read_b64 v[112:113], v4 offset:2624
	ds_read_b64 v[114:115], v4 offset:2656
	ds_read_b128 v[124:127], v6
	ds_read_b128 v[128:131], v6 offset:64
	ds_read_b128 v[132:135], v6 offset:128
	ds_read_b128 v[136:139], v6 offset:192
	s_waitcnt lgkmcnt(15)
	v_mfma_f32_16x16x32_bf16 v[76:79], v[44:47], v[28:31], 0
	s_waitcnt lgkmcnt(14)
	v_mfma_f32_16x16x32_bf16 v[76:79], v[48:51], v[32:35], v[76:79]
	s_waitcnt lgkmcnt(13)
	v_mfma_f32_16x16x32_bf16 v[76:79], v[52:55], v[36:39], v[76:79]
	s_waitcnt lgkmcnt(12)
	v_mfma_f32_16x16x32_bf16 v[76:79], v[56:59], v[40:43], v[76:79]
	s_branch .Lhg_sc0
.Lhg_lt0_1:
	ds_read_b64 v[100:101], v4
	ds_read_b64 v[102:103], v4 offset:32
	ds_read_b64 v[104:105], v4 offset:64
	ds_read_b64 v[106:107], v4 offset:96
	ds_read_b64 v[108:109], v4 offset:2560
	ds_read_b64 v[110:111], v4 offset:2592
	ds_read_b64 v[112:113], v4 offset:2624
	ds_read_b64 v[114:115], v4 offset:2656
	ds_read_b128 v[124:127], v6
	ds_read_b128 v[128:131], v6 offset:64
	ds_read_b128 v[132:135], v6 offset:128
	ds_read_b128 v[136:139], v6 offset:192
	s_waitcnt lgkmcnt(15)
	v_mfma_f32_16x16x32_bf16 v[80:83], v[60:63], v[28:31], 0
	s_waitcnt lgkmcnt(14)
	v_mfma_f32_16x16x32_bf16 v[80:83], v[64:67], v[32:35], v[80:83]
	s_waitcnt lgkmcnt(13)
	v_mfma_f32_16x16x32_bf16 v[80:83], v[68:71], v[36:39], v[80:83]
	s_waitcnt lgkmcnt(12)
	v_mfma_f32_16x16x32_bf16 v[80:83], v[72:75], v[40:43], v[80:83]
	s_branch .Lhg_sc0
.Lhg_lt0_2:
	ds_read_b64 v[100:101], v4
	ds_read_b64 v[102:103], v4 offset:32
	ds_read_b64 v[104:105], v4 offset:64
	ds_read_b64 v[106:107], v4 offset:96
	ds_read_b64 v[108:109], v4 offset:2560
	ds_read_b64 v[110:111], v4 offset:2592
	ds_read_b64 v[112:113], v4 offset:2624
	ds_read_b64 v[114:115], v4 offset:2656
	ds_read_b128 v[124:127], v6
	ds_read_b128 v[128:131], v6 offset:64
	ds_read_b128 v[132:135], v6 offset:128
	ds_read_b128 v[136:139], v6 offset:192
	s_waitcnt lgkmcnt(15)
	v_mfma_f32_16x16x32_bf16 v[84:87], v[44:47], v[28:31], 0
	s_waitcnt lgkmcnt(14)
	v_mfma_f32_16x16x32_bf16 v[84:87], v[48:51], v[32:35], v[84:87]
	s_waitcnt lgkmcnt(13)
	v_mfma_f32_16x16x32_bf16 v[84:87], v[52:55], v[36:39], v[84:87]
	s_waitcnt lgkmcnt(12)
	v_mfma_f32_16x16x32_bf16 v[84:87], v[56:59], v[40:43], v[84:87]
.Lhg_sc0:
	ds_read_b128 v[140:143], v6 offset:4608
	ds_read_b128 v[144:147], v6 offset:4672
	ds_read_b128 v[148:151], v6 offset:4736
	ds_read_b128 v[152:155], v6 offset:4800
	s_nop 7
	s_cmp_lg_u32 s7, 0
	s_cbranch_scc1 .Lhg_nm0_0
	v_cndmask_b32_e64 v76, 0, v76, s[18:19]
	v_cndmask_b32_e64 v77, 0, v77, s[20:21]
	v_cndmask_b32_e64 v78, 0, v78, s[22:23]
	v_cndmask_b32_e64 v79, 0, v79, s[24:25]

.Lhg_pk0:
	ds_read_b64_tr_b16 v[156:157], v8
	ds_read_b64_tr_b16 v[158:159], v8 offset:1152
	ds_read_b64_tr_b16 v[160:161], v8 offset:9216
	ds_read_b64_tr_b16 v[162:163], v8 offset:10368
	ds_read_b64_tr_b16 v[164:165], v8 offset:32
	ds_read_b64_tr_b16 v[166:167], v8 offset:1184
	ds_read_b64_tr_b16 v[168:169], v8 offset:9248
	ds_read_b64_tr_b16 v[170:171], v8 offset:10400
	ds_read_b128 v[176:179], v5
	ds_read_b128 v[180:183], v5 offset:64
	ds_read_b128 v[184:187], v5 offset:2560
	ds_read_b128 v[188:191], v5 offset:2624
	ds_read_b128 v[192:195], v12
	ds_read_b128 v[196:199], v12 offset:64
	s_waitcnt lgkmcnt(14)
	s_nop 0
	v_mfma_f32_16x16x32_bf16 v[116:119], v[100:103], v[92:95], 0
	v_mfma_f32_16x16x32_bf16 v[120:123], v[108:111], v[92:95], 0
	v_mfma_f32_16x16x32_bf16 v[116:119], v[104:107], v[96:99], v[116:119]
	v_mfma_f32_16x16x32_bf16 v[120:123], v[112:115], v[96:99], v[120:123]
	v_mfma_f32_16x16x32_bf16 v[116:119], v[124:127], v[28:31], v[116:119]
	v_mfma_f32_16x16x32_bf16 v[120:123], v[140:143], v[28:31], v[120:123]
	v_mfma_f32_16x16x32_bf16 v[116:119], v[128:131], v[32:35], v[116:119]
	v_mfma_f32_16x16x32_bf16 v[120:123], v[144:147], v[32:35], v[120:123]
	v_mfma_f32_16x16x32_bf16 v[116:119], v[132:135], v[36:39], v[116:119]
	v_mfma_f32_16x16x32_bf16 v[120:123], v[148:151], v[36:39], v[120:123]
	v_mfma_f32_16x16x32_bf16 v[116:119], v[136:139], v[40:43], v[116:119]
	v_mfma_f32_16x16x32_bf16 v[120:123], v[152:155], v[40:43], v[120:123]
	s_waitcnt lgkmcnt(0)
	v_mfma_f32_16x16x32_bf16 v[200:203], v[156:159], v[176:179], v[200:203]
	v_mfma_f32_16x16x32_bf16 v[204:207], v[156:159], v[184:187], v[204:207]
	v_mfma_f32_16x16x32_bf16 v[208:211], v[164:167], v[176:179], v[208:211]
	v_mfma_f32_16x16x32_bf16 v[212:215], v[164:167], v[184:187], v[212:215]
	v_mfma_f32_16x16x32_bf16 v[200:203], v[160:163], v[180:183], v[200:203]
	v_mfma_f32_16x16x32_bf16 v[204:207], v[160:163], v[188:191], v[204:207]
	v_mfma_f32_16x16x32_bf16 v[208:211], v[168:171], v[180:183], v[208:211]
	v_mfma_f32_16x16x32_bf16 v[212:215], v[168:171], v[188:191], v[212:215]
	v_cvt_pk_bf16_f32 v216, v116, v117
	v_cvt_pk_bf16_f32 v217, v118, v119
	v_cvt_pk_bf16_f32 v218, v120, v121
	v_cvt_pk_bf16_f32 v219, v122, v123
	global_store_dwordx2 v[14:15], v[216:217], off
	global_store_dwordx2 v[14:15], v[218:219], off offset:32
	v_lshl_add_u64 v[14:15], v[14:15], 0, s[26:27]
	global_load_dwordx4 v[22:25], v16, s[8:9]
	s_cmp_lt_u32 s16, 63
	s_cselect_b32 s34, s10, 0
	s_cselect_b32 s35, s11, 0
	s_add_u32 s8, s8, s34
	s_addc_u32 s9, s9, s35
	s_add_i32 s16, s16, 1
	s_nop 1
	v_pk_mul_f32 v[200:201], v[200:201], v[192:193]
	v_pk_mul_f32 v[202:203], v[202:203], v[194:195]
	v_pk_mul_f32 v[204:205], v[204:205], v[192:193]
	v_pk_mul_f32 v[206:207], v[206:207], v[194:195]
	v_pk_mul_f32 v[208:209], v[208:209], v[196:197]
	v_pk_mul_f32 v[210:211], v[210:211], v[198:199]
	v_pk_mul_f32 v[212:213], v[212:213], v[196:197]
	v_pk_mul_f32 v[214:215], v[214:215], v[198:199]
	v_cvt_pk_bf16_f32 v220, v200, v201
	v_cvt_pk_bf16_f32 v221, v202, v203
	ds_write_b64 v7, v[220:221] offset:9216
	v_cvt_pk_bf16_f32 v222, v204, v205
	v_cvt_pk_bf16_f32 v223, v206, v207
	ds_write_b64 v7, v[222:223] offset:13824
	v_cvt_pk_bf16_f32 v224, v208, v209
	v_cvt_pk_bf16_f32 v225, v210, v211
	ds_write_b64 v7, v[224:225] offset:9248
	v_cvt_pk_bf16_f32 v226, v212, v213
	v_cvt_pk_bf16_f32 v227, v214, v215
	ds_write_b64 v7, v[226:227] offset:13856
	s_waitcnt lgkmcnt(0)
	s_barrier
	s_waitcnt vmcnt(3)
	ds_write_b16 v17, v18
	ds_write_b16_d16_hi v17, v18 offset:160
	ds_write_b16 v17, v19 offset:320
	ds_write_b16_d16_hi v17, v19 offset:480
	ds_write_b16 v17, v20 offset:640
	ds_write_b16_d16_hi v17, v20 offset:800
	ds_write_b16 v17, v21 offset:960
	ds_write_b16_d16_hi v17, v21 offset:1120
	ds_read_b128 v[28:31], v2 offset:18432
	ds_read_b128 v[32:35], v2 offset:18496
	ds_read_b128 v[36:39], v2 offset:18560
	ds_read_b128 v[40:43], v2 offset:18624
	ds_read_b128 v[44:47], v3 offset:18432
	ds_read_b128 v[48:51], v3 offset:18496
	ds_read_b128 v[52:55], v3 offset:18560
	ds_read_b128 v[56:59], v3 offset:18624
	s_cmp_eq_u32 s7, 0
	s_cbranch_scc1 .Lhg_lt1_0
	ds_read_b128 v[60:63], v3 offset:23040
	ds_read_b128 v[64:67], v3 offset:23104
	ds_read_b128 v[68:71], v3 offset:23168
	ds_read_b128 v[72:75], v3 offset:23232
	s_waitcnt lgkmcnt(7)
	v_mfma_f32_16x16x32_bf16 v[76:79], v[44:47], v[28:31], 0
	s_waitcnt lgkmcnt(6)
	v_mfma_f32_16x16x32_bf16 v[76:79], v[48:51], v[32:35], v[76:79]
	s_waitcnt lgkmcnt(5)
	v_mfma_f32_16x16x32_bf16 v[76:79], v[52:55], v[36:39], v[76:79]
	s_waitcnt lgkmcnt(4)
	v_mfma_f32_16x16x32_bf16 v[76:79], v[56:59], v[40:43], v[76:79]
	s_cmp_eq_u32 s7, 1
	s_cbranch_scc1 .Lhg_lt1_1
	ds_read_b128 v[44:47], v3 offset:27648
	ds_read_b128 v[48:51], v3 offset:27712
	ds_read_b128 v[52:55], v3 offset:27776
	ds_read_b128 v[56:59], v3 offset:27840
	s_waitcnt lgkmcnt(7)
	v_mfma_f32_16x16x32_bf16 v[80:83], v[60:63], v[28:31], 0
	s_waitcnt lgkmcnt(6)
	v_mfma_f32_16x16x32_bf16 v[80:83], v[64:67], v[32:35], v[80:83]
	s_waitcnt lgkmcnt(5)
	v_mfma_f32_16x16x32_bf16 v[80:83], v[68:71], v[36:39], v[80:83]
	s_waitcnt lgkmcnt(4)
	v_mfma_f32_16x16x32_bf16 v[80:83], v[72:75], v[40:43], v[80:83]
	s_cmp_eq_u32 s7, 2
	s_cbranch_scc1 .Lhg_lt1_2
	ds_read_b128 v[60:63], v3 offset:32256
	ds_read_b128 v[64:67], v3 offset:32320
	ds_read_b128 v[68:71], v3 offset:32384
	ds_read_b128 v[72:75], v3 offset:32448
	s_waitcnt lgkmcnt(7)
	v_mfma_f32_16x16x32_bf16 v[84:87], v[44:47], v[28:31], 0
	s_waitcnt lgkmcnt(6)
	v_mfma_f32_16x16x32_bf16 v[84:87], v[48:51], v[32:35], v[84:87]
	s_waitcnt lgkmcnt(5)
	v_mfma_f32_16x16x32_bf16 v[84:87], v[52:55], v[36:39], v[84:87]
	s_waitcnt lgkmcnt(4)
	v_mfma_f32_16x16x32_bf16 v[84:87], v[56:59], v[40:43], v[84:87]
	ds_read_b64 v[100:101], v4 offset:5120
	ds_read_b64 v[102:103], v4 offset:5152
	ds_read_b64 v[104:105], v4 offset:5184
	ds_read_b64 v[106:107], v4 offset:5216
	ds_read_b64 v[108:109], v4 offset:7680
	ds_read_b64 v[110:111], v4 offset:7712
	ds_read_b64 v[112:113], v4 offset:7744
	ds_read_b64 v[114:115], v4 offset:7776
	ds_read_b128 v[124:127], v6 offset:9216
	ds_read_b128 v[128:131], v6 offset:9280
	ds_read_b128 v[132:135], v6 offset:9344
	ds_read_b128 v[136:139], v6 offset:9408
	s_waitcnt lgkmcnt(15)
	v_mfma_f32_16x16x32_bf16 v[88:91], v[60:63], v[28:31], 0
	s_waitcnt lgkmcnt(14)
	v_mfma_f32_16x16x32_bf16 v[88:91], v[64:67], v[32:35], v[88:91]
	s_waitcnt lgkmcnt(13)
	v_mfma_f32_16x16x32_bf16 v[88:91], v[68:71], v[36:39], v[88:91]
	s_waitcnt lgkmcnt(12)
	v_mfma_f32_16x16x32_bf16 v[88:91], v[72:75], v[40:43], v[88:91]
	s_branch .Lhg_sc1
.Lhg_lt1_0:
	ds_read_b64 v[100:101], v4 offset:5120
	ds_read_b64 v[102:103], v4 offset:5152
	ds_read_b64 v[104:105], v4 offset:5184
	ds_read_b64 v[106:107], v4 offset:5216
	ds_read_b64 v[108:109], v4 offset:7680
	ds_read_b64 v[110:111], v4 offset:7712
	ds_read_b64 v[112:113], v4 offset:7744
	ds_read_b64 v[114:115], v4 offset:7776
	ds_read_b128 v[124:127], v6 offset:9216
	ds_read_b128 v[128:131], v6 offset:9280
	ds_read_b128 v[132:135], v6 offset:9344
	ds_read_b128 v[136:139], v6 offset:9408
	s_waitcnt lgkmcnt(15)
	v_mfma_f32_16x16x32_bf16 v[76:79], v[44:47], v[28:31], 0
	s_waitcnt lgkmcnt(14)
	v_mfma_f32_16x16x32_bf16 v[76:79], v[48:51], v[32:35], v[76:79]
	s_waitcnt lgkmcnt(13)
	v_mfma_f32_16x16x32_bf16 v[76:79], v[52:55], v[36:39], v[76:79]
	s_waitcnt lgkmcnt(12)
	v_mfma_f32_16x16x32_bf16 v[76:79], v[56:59], v[40:43], v[76:79]
	s_branch .Lhg_sc1
.Lhg_lt1_1:
	ds_read_b64 v[100:101], v4 offset:5120
	ds_read_b64 v[102:103], v4 offset:5152
	ds_read_b64 v[104:105], v4 offset:5184
	ds_read_b64 v[106:107], v4 offset:5216
	ds_read_b64 v[108:109], v4 offset:7680
	ds_read_b64 v[110:111], v4 offset:7712
	ds_read_b64 v[112:113], v4 offset:7744
	ds_read_b64 v[114:115], v4 offset:7776
	ds_read_b128 v[124:127], v6 offset:9216
	ds_read_b128 v[128:131], v6 offset:9280
	ds_read_b128 v[132:135], v6 offset:9344
	ds_read_b128 v[136:139], v6 offset:9408
	s_waitcnt lgkmcnt(15)
	v_mfma_f32_16x16x32_bf16 v[80:83], v[60:63], v[28:31], 0
	s_waitcnt lgkmcnt(14)
	v_mfma_f32_16x16x32_bf16 v[80:83], v[64:67], v[32:35], v[80:83]
	s_waitcnt lgkmcnt(13)
	v_mfma_f32_16x16x32_bf16 v[80:83], v[68:71], v[36:39], v[80:83]
	s_waitcnt lgkmcnt(12)
	v_mfma_f32_16x16x32_bf16 v[80:83], v[72:75], v[40:43], v[80:83]
	s_branch .Lhg_sc1
.Lhg_lt1_2:
	ds_read_b64 v[100:101], v4 offset:5120
	ds_read_b64 v[102:103], v4 offset:5152
	ds_read_b64 v[104:105], v4 offset:5184
	ds_read_b64 v[106:107], v4 offset:5216
	ds_read_b64 v[108:109], v4 offset:7680
	ds_read_b64 v[110:111], v4 offset:7712
	ds_read_b64 v[112:113], v4 offset:7744
	ds_read_b64 v[114:115], v4 offset:7776
	ds_read_b128 v[124:127], v6 offset:9216
	ds_read_b128 v[128:131], v6 offset:9280
	ds_read_b128 v[132:135], v6 offset:9344
	ds_read_b128 v[136:139], v6 offset:9408
	s_waitcnt lgkmcnt(15)
	v_mfma_f32_16x16x32_bf16 v[84:87], v[44:47], v[28:31], 0
	s_waitcnt lgkmcnt(14)
	v_mfma_f32_16x16x32_bf16 v[84:87], v[48:51], v[32:35], v[84:87]
	s_waitcnt lgkmcnt(13)
	v_mfma_f32_16x16x32_bf16 v[84:87], v[52:55], v[36:39], v[84:87]
	s_waitcnt lgkmcnt(12)
	v_mfma_f32_16x16x32_bf16 v[84:87], v[56:59], v[40:43], v[84:87]
.Lhg_sc1:
	ds_read_b128 v[140:143], v6 offset:13824
	ds_read_b128 v[144:147], v6 offset:13888
	ds_read_b128 v[148:151], v6 offset:13952
	ds_read_b128 v[152:155], v6 offset:14016
	s_nop 7
	s_cmp_lg_u32 s7, 0
	s_cbranch_scc1 .Lhg_nm1_0
	v_cndmask_b32_e64 v76, 0, v76, s[18:19]
	v_cndmask_b32_e64 v77, 0, v77, s[20:21]
	v_cndmask_b32_e64 v78, 0, v78, s[22:23]
	v_cndmask_b32_e64 v79, 0, v79, s[24:25]

.Lhg_pk1:
	ds_read_b64_tr_b16 v[156:157], v8 offset:18432
	ds_read_b64_tr_b16 v[158:159], v8 offset:19584
	ds_read_b64_tr_b16 v[160:161], v8 offset:27648
	ds_read_b64_tr_b16 v[162:163], v8 offset:28800
	ds_read_b64_tr_b16 v[164:165], v8 offset:18464
	ds_read_b64_tr_b16 v[166:167], v8 offset:19616
	ds_read_b64_tr_b16 v[168:169], v8 offset:27680
	ds_read_b64_tr_b16 v[170:171], v8 offset:28832
	ds_read_b128 v[176:179], v5 offset:5120
	ds_read_b128 v[180:183], v5 offset:5184
	ds_read_b128 v[184:187], v5 offset:7680
	ds_read_b128 v[188:191], v5 offset:7744
	ds_read_b128 v[192:195], v12 offset:512
	ds_read_b128 v[196:199], v12 offset:576
	s_waitcnt lgkmcnt(14)
	s_nop 0
	v_mfma_f32_16x16x32_bf16 v[116:119], v[100:103], v[92:95], 0
	v_mfma_f32_16x16x32_bf16 v[120:123], v[108:111], v[92:95], 0
	v_mfma_f32_16x16x32_bf16 v[116:119], v[104:107], v[96:99], v[116:119]
	v_mfma_f32_16x16x32_bf16 v[120:123], v[112:115], v[96:99], v[120:123]
	v_mfma_f32_16x16x32_bf16 v[116:119], v[124:127], v[28:31], v[116:119]
	v_mfma_f32_16x16x32_bf16 v[120:123], v[140:143], v[28:31], v[120:123]
	v_mfma_f32_16x16x32_bf16 v[116:119], v[128:131], v[32:35], v[116:119]
	v_mfma_f32_16x16x32_bf16 v[120:123], v[144:147], v[32:35], v[120:123]
	v_mfma_f32_16x16x32_bf16 v[116:119], v[132:135], v[36:39], v[116:119]
	v_mfma_f32_16x16x32_bf16 v[120:123], v[148:151], v[36:39], v[120:123]
	v_mfma_f32_16x16x32_bf16 v[116:119], v[136:139], v[40:43], v[116:119]
	v_mfma_f32_16x16x32_bf16 v[120:123], v[152:155], v[40:43], v[120:123]
	s_waitcnt lgkmcnt(0)
	v_mfma_f32_16x16x32_bf16 v[200:203], v[156:159], v[176:179], v[200:203]
	v_mfma_f32_16x16x32_bf16 v[204:207], v[156:159], v[184:187], v[204:207]
	v_mfma_f32_16x16x32_bf16 v[208:211], v[164:167], v[176:179], v[208:211]
	v_mfma_f32_16x16x32_bf16 v[212:215], v[164:167], v[184:187], v[212:215]
	v_mfma_f32_16x16x32_bf16 v[200:203], v[160:163], v[180:183], v[200:203]
	v_mfma_f32_16x16x32_bf16 v[204:207], v[160:163], v[188:191], v[204:207]
	v_mfma_f32_16x16x32_bf16 v[208:211], v[168:171], v[180:183], v[208:211]
	v_mfma_f32_16x16x32_bf16 v[212:215], v[168:171], v[188:191], v[212:215]
	v_cvt_pk_bf16_f32 v216, v116, v117
	v_cvt_pk_bf16_f32 v217, v118, v119
	v_cvt_pk_bf16_f32 v218, v120, v121
	v_cvt_pk_bf16_f32 v219, v122, v123
	global_store_dwordx2 v[14:15], v[216:217], off
	global_store_dwordx2 v[14:15], v[218:219], off offset:32
	v_lshl_add_u64 v[14:15], v[14:15], 0, s[26:27]
	global_load_dwordx4 v[18:21], v16, s[8:9]
	s_cmp_lt_u32 s16, 63
	s_cselect_b32 s34, s10, 0
	s_cselect_b32 s35, s11, 0
	s_add_u32 s8, s8, s34
	s_addc_u32 s9, s9, s35
	s_add_i32 s16, s16, 1
	s_nop 1
	v_pk_mul_f32 v[200:201], v[200:201], v[192:193]
	v_pk_mul_f32 v[202:203], v[202:203], v[194:195]
	v_pk_mul_f32 v[204:205], v[204:205], v[192:193]
	v_pk_mul_f32 v[206:207], v[206:207], v[194:195]
	v_pk_mul_f32 v[208:209], v[208:209], v[196:197]
	v_pk_mul_f32 v[210:211], v[210:211], v[198:199]
	v_pk_mul_f32 v[212:213], v[212:213], v[196:197]
	v_pk_mul_f32 v[214:215], v[214:215], v[198:199]
	v_cvt_pk_bf16_f32 v220, v200, v201
	v_cvt_pk_bf16_f32 v221, v202, v203
	ds_write_b64 v7, v[220:221]
	v_cvt_pk_bf16_f32 v222, v204, v205
	v_cvt_pk_bf16_f32 v223, v206, v207
	ds_write_b64 v7, v[222:223] offset:4608
	v_cvt_pk_bf16_f32 v224, v208, v209
	v_cvt_pk_bf16_f32 v225, v210, v211
	ds_write_b64 v7, v[224:225] offset:32
	v_cvt_pk_bf16_f32 v226, v212, v213
	v_cvt_pk_bf16_f32 v227, v214, v215
	ds_write_b64 v7, v[226:227] offset:4640
	s_waitcnt lgkmcnt(0)
	s_barrier
	s_add_i32 s17, s17, -1
	s_cmp_lg_u32 s17, 0
	s_cbranch_scc1 .Lhg_sloop
